# flat->global, FoX vote flags via ds ops, mixer queue reordered: scans start after 35 chunks of preps
# speedup vs baseline: 1.0150x; 1.0150x over previous
; __device__ __forceinline__ int my_tid() { int t = (int)threadIdx.x; asm volatile("" : "+v"(t)); return t; }
; __device__ __forceinline__ int fetch_item(unsigned* ctr, unsigned char* lds) {
;     volatile int* slot = (volatile int*)(lds + LDS_SLOT);
;     __syncthreads();
;     if (my_tid() == 0) *slot = (int)atomicAdd(ctr, 1u);
;     __syncthreads();
;     return *slot;
; }
; __device__ void run_phase(const Params& p, unsigned char* lds, int ph) {
;     ...
;         for (;;) {
;             const int it = fetch_item(ctr, lds);
;             if (it >= 3120) break;
;             if (it < 16) { const int bh = it;
;                 fcum_unit(lds, bh, (const float*)(ws + WS_SCAL), p.in[I_FGB] + l * 4, (float*)(ws + WS_F) , (const bf16_t*)(ws + WS_PAB) + (size_t)(bh >> 2) * SEQ * 1536 + 1024 + (bh & 3) * 64, (float*)(ws + WS_KN) + bh * 128, (const bf16_t*)(ws + WS_PAB) + (size_t)(bh >> 2) * SEQ * 1536 + 256 + (bh & 3) * 64, p.in[I_REL] + (size_t)(l * 4 + (bh & 3)) * 320, (float*)(ws + WS_AB) + bh * 2, uflag + 2048 + bh, fval); }
;             else if (it < 48) { const int j = it - 16;
;                 for (int rep = 0; rep < REP_SCAN; ++rep) { scan_unit(lds, j >> 1, j & 1, ws + WS_PREP, (const float*)(ws + WS_EGL), uflag + (j >> 1) * 128, fval); __syncthreads(); } }
;             else if (it < 2096) { const int j = it - 48, n = j >> 4, bh = j & 15, h = bh & 3;
;                 prep_unit(lds, bh, n, (const bf16_t*)(ws + WS_PC), (const float*)(ws + WS_SCAL), p.in[I_CONVW] + (size_t)l * 4 * 1536, p.in[I_ALOG][l * 4 + h], p.in[I_DTB][l * 4 + h],
;                           ws + WS_PREP + (size_t)(bh * 128 + n) * PREP_UNIT, (float*)(ws + WS_EGL), uflag + bh * 128 + n, fval); }
;             else if (it < 2608) { const int j = it - 2096, qb = j & 31, bh = j >> 5, b = bh >> 2, h = bh & 3;
;                 for (int rep = 0; rep < REP_A; ++rep) { attn_unit<1>(lds, b, qb, pab + h * 64, pab + 256 + h * 64, pab + 512 + h * 64, 1536, hbuf + h * 64, DM, nullptr, p.in[I_REL] + (size_t)(l * 4 + h) * 320, (const float*)(ws + WS_AB) + bh * 2, uflag + 2048 + bh, fval); __syncthreads(); } }
;             else { const int j = it - 2608, qb = 31 - (j >> 4), bh = j & 15, b = bh >> 2, h = bh & 3;
.LBB0_174:
	v_mov_b32_e32 v0, v212
	s_waitcnt lgkmcnt(0)
	s_barrier
	s_nop 0
	v_cmp_eq_u32_e32 vcc, 0, v0
	s_and_saveexec_b64 s[0:1], vcc
	s_cbranch_execz .LBB0_176
	v_readlane_b32 s4, v255, 7
	v_readlane_b32 s5, v255, 8
	s_mov_b64 s[2:3], src_shared_base
	s_add_i32 s2, 0, 0x26400
	s_waitcnt vmcnt(0)
	v_mov_b64_e32 v[2:3], s[4:5]
	global_atomic_add v0, v[2:3], v214, off offset:32 sc0
	s_cmp_lg_u32 s2, -1
	s_cselect_b32 s2, s2, 0
	s_cselect_b32 s3, s3, 0
	v_mov_b32_e32 v2, s2
	v_mov_b32_e32 v3, s3
	s_waitcnt vmcnt(0) lgkmcnt(0)
	ds_write_b32 v2, v0
	s_waitcnt vmcnt(0)
.LBB0_176:
	s_or_b64 exec, exec, s[0:1]
	s_mov_b64 s[0:1], src_shared_base
	s_add_i32 s0, 0, 0x26400
	s_cmp_lg_u32 s0, -1
	s_cselect_b32 s0, s0, 0
	s_cselect_b32 s1, s1, 0
	s_waitcnt vmcnt(0)
	v_mov_b32_e32 v2, s0
	v_mov_b32_e32 v3, s1
	s_waitcnt lgkmcnt(0)
	s_barrier
	ds_read_b32 v90, v2
	s_waitcnt vmcnt(0)
	s_movk_i32 s0, 0xc30
	s_waitcnt lgkmcnt(0)
	v_add_u32_e32 v2, 32, v90
	v_subrev_u32_e32 v3, 560, v90
	v_cmp_gt_u32_e32 vcc, 576, v90
	s_nop 1
	v_cndmask_b32_e32 v3, v3, v2, vcc
	v_add_u32_e32 v2, -16, v90
	v_cmp_gt_u32_e32 vcc, 592, v2
	s_nop 1
	v_cndmask_b32_e32 v90, v90, v3, vcc
	s_nop 1
	v_cmp_gt_i32_e32 vcc, s0, v90
	s_mov_b64 s[0:1], -1
	s_and_saveexec_b64 s[30:31], vcc
	s_cbranch_execz .LBB0_173
	v_cmp_lt_i32_e32 vcc, 15, v90
	s_and_saveexec_b64 s[0:1], vcc
	s_xor_b64 s[4:5], exec, s[0:1]
	s_cbranch_execz .LBB0_620
	s_mov_b64 s[56:57], s[4:5]
	v_cmp_lt_u32_e32 vcc, 47, v90
	s_and_saveexec_b64 s[0:1], vcc
	s_xor_b64 s[4:5], exec, s[0:1]
	s_cbranch_execz .LBB0_450
	v_writelane_b32 v255, s4, 45
	s_movk_i32 s0, 0x82f
	v_cmp_lt_u32_e32 vcc, s0, v90
	v_writelane_b32 v255, s5, 46
	s_and_saveexec_b64 s[0:1], vcc
	s_xor_b64 s[0:1], exec, s[0:1]
	s_cbranch_execz .LBB0_302
	v_writelane_b32 v255, s0, 47
	s_nop 1
	v_writelane_b32 v255, s1, 48
	s_movk_i32 s0, 0xa2f
	v_cmp_lt_u32_e32 vcc, s0, v90
	s_and_saveexec_b64 s[0:1], vcc
	s_xor_b64 s[0:1], exec, s[0:1]
	v_writelane_b32 v255, s0, 49
	s_nop 1
	v_writelane_b32 v255, s1, 50
	s_cbranch_execz .LBB0_257
	v_and_b32_e32 v6, 15, v90
	v_mov_b32_e32 v146, v212
	s_mov_b64 s[0:1], exec
	v_readlane_b32 s2, v254, 1
	v_readlane_b32 s3, v254, 2
	s_and_b64 s[2:3], s[0:1], s[2:3]
	s_mov_b64 exec, s[2:3]
	s_cbranch_execz .LBB0_186
	v_readlane_b32 s2, v255, 27
	v_lshlrev_b32_e32 v0, 2, v6
	v_readlane_b32 s3, v255, 28
	s_nop 1
	v_lshl_add_u64 v[2:3], s[2:3], 0, v[0:1]
	global_load_dword v0, v[2:3], off sc1
	s_waitcnt vmcnt(0) lgkmcnt(0)
	v_cmp_gt_u32_e32 vcc, s73, v0
	s_and_saveexec_b64 s[2:3], vcc
	s_cbranch_execz .LBB0_185
	s_mov_b64 s[4:5], 0

.LBB0_211:
	s_or_b64 exec, exec, s[2:3]
	v_cndmask_b32_e64 v0, 0, 1, s[8:9]
	s_mov_b64 s[4:5], exec
	v_cmp_ne_u32_e64 s[0:1], 0, v0
	s_and_saveexec_b64 s[2:3], s[6:7]
	s_cbranch_execz .LBB0_213
	s_mov_b64 s[8:9], src_shared_base
	s_and_b32 s8, s41, 8
	s_cmp_eq_u64 s[0:1], s[4:5]
	v_lshl_add_u32 v0, s8, 2, v196
	s_cselect_b64 s[0:1], -1, 0
	v_add_u32_e32 v82, 0xa400, v0
	v_mov_b32_e32 v83, s9
	v_cndmask_b32_e64 v0, 0, 1, s[0:1]
	ds_write_b32 v82, v0
	s_waitcnt vmcnt(0)

.LBB0_216:
	s_or_b64 exec, exec, s[2:3]
	s_and_b32 s0, s41, 8
	s_lshl_b32 s0, s0, 2
	s_add_i32 s43, s0, 0
	s_mov_b64 s[36:37], src_shared_base
	s_add_i32 s38, s43, 0xa400
	s_mov_b32 s39, s37
	v_mov_b64_e32 v[82:83], s[38:39]
	s_add_i32 s36, s43, 0xa404
	s_waitcnt lgkmcnt(0)
	s_barrier
	ds_read_b128 v[84:87], v82
	ds_read_b128 v[88:91], v82 offset:16
	s_waitcnt vmcnt(0) lgkmcnt(0)
	v_cmp_ne_u32_e64 s[8:9], 0, v90
	v_cmp_ne_u32_e64 s[0:1], 0, v91
	s_and_b64 s[4:5], s[0:1], s[8:9]
	v_cmp_ne_u32_e64 s[0:1], 0, v89
	s_and_b64 s[4:5], s[4:5], s[0:1]
	v_cmp_ne_u32_e64 s[0:1], 0, v88
	s_and_b64 s[4:5], s[4:5], s[0:1]
	v_cmp_ne_u32_e64 s[0:1], 0, v87
	s_and_b64 s[4:5], s[4:5], s[0:1]
	v_cmp_ne_u32_e64 s[0:1], 0, v86
	s_and_b64 s[4:5], s[4:5], s[0:1]
	v_cmp_ne_u32_e64 s[0:1], 0, v85
	s_and_b64 s[4:5], s[4:5], s[0:1]
	v_cmp_ne_u32_e64 s[0:1], 0, v84
	s_and_b64 s[34:35], s[4:5], s[0:1]
	s_xor_b64 s[4:5], s[34:35], -1
	v_cmp_lt_u32_e64 s[0:1], v0, v189
	s_and_b64 s[0:1], s[0:1], s[4:5]
	s_and_saveexec_b64 s[4:5], s[0:1]
	s_cbranch_execz .LBB0_235
	v_cmp_lt_u32_e64 s[0:1], v202, v180
	s_and_saveexec_b64 s[8:9], s[0:1]
	s_cbranch_execz .LBB0_221
	v_add_u32_e32 v42, 1, v178
	v_ashrrev_i32_e32 v43, 31, v42
	v_lshlrev_b64 v[42:43], 6, v[42:43]
	v_lshl_add_u64 v[42:43], v[42:43], 0, v[154:155]
	v_lshl_add_u64 v[44:45], v[42:43], 0, v[162:163]
	v_or_b32_e32 v42, v42, v156
	v_mad_u64_u32 v[46:47], s[0:1], v44, s53, v[166:167]
	v_mad_u64_u32 v[48:49], s[0:1], v42, s53, v[168:169]
	v_mad_i32_i24 v47, v45, s53, v47
	v_mad_i32_i24 v49, v43, s53, v49
	global_load_dwordx4 v[42:45], v[46:47], off
	s_nop 0
	global_load_dwordx4 v[46:49], v[48:49], off
	s_and_saveexec_b64 s[0:1], vcc
	s_cbranch_execz .LBB0_220
	s_movk_i32 s10, 0xfec1
	v_add3_u32 v82, v146, v200, s10
	v_ashrrev_i32_e32 v83, 31, v82
	v_lshl_add_u64 v[82:83], v[82:83], 2, v[148:149]
	global_load_dword v182, v[82:83], off

.LBB0_229:
	s_or_b64 exec, exec, s[8:9]
	v_cndmask_b32_e64 v0, 0, 1, s[12:13]
	s_mov_b64 s[10:11], exec
	v_cmp_ne_u32_e64 s[0:1], 0, v0
	s_and_saveexec_b64 s[8:9], s[6:7]
	s_cbranch_execz .LBB0_231
	s_add_i32 s12, s41, 8
	s_and_b32 s12, s12, 8
	s_cmp_eq_u64 s[0:1], s[10:11]
	v_lshl_add_u32 v0, s12, 2, v196
	s_mov_b64 s[12:13], src_shared_base
	s_cselect_b64 s[0:1], -1, 0
	v_add_u32_e32 v82, 0xa400, v0
	v_mov_b32_e32 v83, s13
	v_cndmask_b32_e64 v0, 0, 1, s[0:1]
	ds_write_b32 v82, v0
	s_waitcnt vmcnt(0)

.LBB0_234:
	s_or_b64 exec, exec, s[8:9]
	s_add_i32 s0, s41, 8
	s_and_b32 s0, s0, 8
	s_lshl_b32 s0, s0, 2
	s_add_i32 s20, s0, 0
	s_add_i32 s8, s20, 0xa400
	s_mov_b64 s[0:1], src_shared_base
	v_mov_b32_e32 v82, s8
	v_mov_b32_e32 v83, s1
	s_waitcnt lgkmcnt(0)
	s_barrier
	ds_read_b128 v[84:87], v82
	ds_read_b128 v[88:91], v82 offset:16
	s_waitcnt vmcnt(0) lgkmcnt(0)
	v_cmp_ne_u32_e64 s[0:1], 0, v84
	v_cmp_ne_u32_e64 s[8:9], 0, v85
	v_cmp_ne_u32_e64 s[10:11], 0, v86
	v_cmp_ne_u32_e64 s[12:13], 0, v87
	v_cmp_ne_u32_e64 s[14:15], 0, v88
	v_cmp_ne_u32_e64 s[16:17], 0, v89
	v_cmp_ne_u32_e64 s[18:19], 0, v90
	v_cmp_ne_u32_e64 s[20:21], 0, v91
	s_and_b64 s[18:19], s[20:21], s[18:19]
	s_and_b64 s[16:17], s[18:19], s[16:17]
	s_and_b64 s[14:15], s[16:17], s[14:15]
	s_and_b64 s[12:13], s[14:15], s[12:13]
	s_and_b64 s[10:11], s[12:13], s[10:11]
	s_and_b64 s[8:9], s[10:11], s[8:9]
	s_and_b64 s[0:1], s[8:9], s[0:1]
	s_andn2_b64 s[8:9], s[34:35], exec
	s_and_b64 s[0:1], s[0:1], exec
	s_or_b64 s[34:35], s[8:9], s[0:1]

.LBB0_248:
	s_or_b64 exec, exec, s[8:9]
	v_cndmask_b32_e64 v0, 0, 1, s[12:13]
	s_mov_b64 s[10:11], exec
	v_cmp_ne_u32_e64 s[0:1], 0, v0
	s_and_saveexec_b64 s[8:9], s[6:7]
	s_cbranch_execz .LBB0_250
	s_cmp_eq_u64 s[0:1], s[10:11]
	v_lshl_add_u32 v0, v153, 2, s43
	s_mov_b64 s[12:13], src_shared_base
	s_cselect_b64 s[0:1], -1, 0
	v_add_u32_e32 v82, 0xa400, v0
	v_mov_b32_e32 v83, s13
	v_cndmask_b32_e64 v0, 0, 1, s[0:1]
	ds_write_b32 v82, v0
	s_waitcnt vmcnt(0)

.LBB0_253:
	s_or_b64 exec, exec, s[8:9]
	v_mov_b64_e32 v[82:83], s[38:39]
	s_waitcnt lgkmcnt(0)
	s_barrier
	ds_read_b128 v[84:87], v82
	ds_read_b128 v[88:91], v82 offset:16
	s_waitcnt vmcnt(0) lgkmcnt(0)
	v_cmp_ne_u32_e64 s[0:1], 0, v84
	v_cmp_ne_u32_e64 s[8:9], 0, v85
	v_cmp_ne_u32_e64 s[10:11], 0, v86
	v_cmp_ne_u32_e64 s[12:13], 0, v87
	v_cmp_ne_u32_e64 s[14:15], 0, v88
	v_cmp_ne_u32_e64 s[16:17], 0, v89
	v_cmp_ne_u32_e64 s[18:19], 0, v90
	v_cmp_ne_u32_e64 s[20:21], 0, v91
	s_and_b64 s[2:3], s[20:21], s[18:19]
	s_and_b64 s[2:3], s[2:3], s[16:17]
	s_and_b64 s[2:3], s[2:3], s[14:15]
	s_and_b64 s[2:3], s[2:3], s[12:13]
	s_and_b64 s[2:3], s[2:3], s[10:11]
	s_and_b64 s[2:3], s[2:3], s[8:9]
	s_and_b64 s[8:9], s[2:3], s[0:1]
